# NA attention mask+bias (2 in-loop instances): 32 branchy exec-masked ds_read/wait/add steps replaced by 15-deep pipelined unconditional LDS reads + v_add + v_cndmask
# baseline (speedup 1.0000x reference)
.LBB0_451:
	v_cndmask_b32_e64 v228, v96, v194, s[16:17]
	v_mul_f32_e32 v196, 0xbe0293ee, v228
	v_mov_b32_e32 v197, v196
	v_pk_fma_f32 v[94:95], v[94:95], s[36:37], v[196:197] op_sel_hi:[1,0,0]
	v_pk_fma_f32 v[92:93], v[92:93], s[36:37], v[196:197] op_sel_hi:[1,0,0]
	v_pk_fma_f32 v[90:91], v[90:91], s[36:37], v[196:197] op_sel_hi:[1,0,0]
	v_pk_fma_f32 v[88:89], v[88:89], s[36:37], v[196:197] op_sel_hi:[1,0,0]
	v_pk_fma_f32 v[86:87], v[86:87], s[36:37], v[196:197] op_sel_hi:[1,0,0]
	v_pk_fma_f32 v[84:85], v[84:85], s[36:37], v[196:197] op_sel_hi:[1,0,0]
	v_pk_fma_f32 v[82:83], v[82:83], s[36:37], v[196:197] op_sel_hi:[1,0,0]
	v_pk_fma_f32 v[80:81], v[80:81], s[36:37], v[196:197] op_sel_hi:[1,0,0]
	v_exp_f32_e32 v192, v82
	v_exp_f32_e32 v194, v80
	v_exp_f32_e32 v195, v81
	v_exp_f32_e32 v193, v83
	v_exp_f32_e32 v190, v84
	v_exp_f32_e32 v191, v85
	v_exp_f32_e32 v188, v86
	v_exp_f32_e32 v189, v87
	v_exp_f32_e32 v186, v88
	v_exp_f32_e32 v187, v89
	v_exp_f32_e32 v184, v90
	v_exp_f32_e32 v185, v91
	v_exp_f32_e32 v182, v92
	v_exp_f32_e32 v183, v93
	v_exp_f32_e32 v174, v94
	v_exp_f32_e32 v175, v95
	s_mov_b32 s29, 0x42b504f3
	s_waitcnt lgkmcnt(0)
	s_barrier
	ds_read_b128 v[80:83], v208 offset:32768
	ds_read_b128 v[198:201], v213 offset:32768
	s_cmp_lt_u32 s37, 3
	s_waitcnt lgkmcnt(1)
	v_mfma_f32_32x32x16_bf16 v[96:111], v[80:83], v[120:123], 0
	ds_read_b128 v[80:83], v208 offset:40960
	s_waitcnt lgkmcnt(1)
	v_mfma_f32_32x32x16_bf16 v[96:111], v[198:201], v[112:115], v[96:111]
	ds_read_b128 v[198:201], v213 offset:40960
	ds_read_b128 v[248:251], v214 offset:32768
	s_waitcnt lgkmcnt(2)
	v_mfma_f32_32x32x16_bf16 v[80:95], v[80:83], v[120:123], 0
	s_waitcnt lgkmcnt(1)
	v_mfma_f32_32x32x16_bf16 v[80:95], v[198:201], v[112:115], v[80:95]
	ds_read_b128 v[198:201], v214 offset:40960
	s_waitcnt lgkmcnt(1)
	v_mfma_f32_32x32x16_bf16 v[96:111], v[248:251], v[132:135], v[96:111]
	ds_read_b128 v[248:251], v215 offset:32768
	s_waitcnt lgkmcnt(1)
	v_mfma_f32_32x32x16_bf16 v[80:95], v[198:201], v[132:135], v[80:95]
	ds_read_b128 v[198:201], v215 offset:40960
	s_waitcnt lgkmcnt(1)
	v_mfma_f32_32x32x16_bf16 v[96:111], v[248:251], v[140:143], v[96:111]
	ds_read_b128 v[248:251], v216 offset:32768
	s_waitcnt lgkmcnt(1)
	v_mfma_f32_32x32x16_bf16 v[80:95], v[198:201], v[140:143], v[80:95]
	ds_read_b128 v[198:201], v216 offset:40960
	s_waitcnt lgkmcnt(1)
	v_mfma_f32_32x32x16_bf16 v[96:111], v[248:251], v[136:139], v[96:111]
	ds_read_b128 v[248:251], v217 offset:32768
	s_waitcnt lgkmcnt(1)
	v_mfma_f32_32x32x16_bf16 v[80:95], v[198:201], v[136:139], v[80:95]
	ds_read_b128 v[198:201], v217 offset:40960
	s_waitcnt lgkmcnt(1)
	v_mfma_f32_32x32x16_bf16 v[96:111], v[248:251], v[128:131], v[96:111]
	ds_read_b128 v[248:251], v218 offset:32768
	s_waitcnt lgkmcnt(1)
	v_mfma_f32_32x32x16_bf16 v[80:95], v[198:201], v[128:131], v[80:95]
	ds_read_b128 v[198:201], v218 offset:40960
	s_waitcnt lgkmcnt(1)
	v_mfma_f32_32x32x16_bf16 v[96:111], v[248:251], v[124:127], v[96:111]
	ds_read_b128 v[248:251], v219 offset:32768
	s_waitcnt lgkmcnt(1)
	v_mfma_f32_32x32x16_bf16 v[80:95], v[198:201], v[124:127], v[80:95]
	ds_read_b128 v[198:201], v219 offset:40960
	s_waitcnt lgkmcnt(1)
	v_mfma_f32_32x32x16_bf16 v[96:111], v[248:251], v[116:119], v[96:111]
	s_waitcnt lgkmcnt(0)
	v_mfma_f32_32x32x16_bf16 v[80:95], v[198:201], v[116:119], v[80:95]
	s_cbranch_scc1 .LBB0_519
	s_add_i32 s1, s33, s39
	s_add_i32 s1, s1, -6
	v_cmp_ge_i32_e32 vcc, s1, v223
	v_cmp_lt_i32_e64 s[16:17], s1, v224
	s_and_b64 s[34:35], vcc, s[16:17]
	v_mov_b32_e32 v180, 0xf149f2ca
	v_mov_b32_e32 v198, 0xf149f2ca
	v_mov_b32_e32 v205, 0xf149f2ca
	v_mov_b32_e32 v178, 0xf149f2ca
	v_mov_b32_e32 v201, 0xf149f2ca
	v_mov_b32_e32 v181, 0xf149f2ca
	v_mov_b32_e32 v199, 0xf149f2ca
	v_mov_b32_e32 v200, 0xf149f2ca
	v_mov_b32_e32 v250, 0xf149f2ca
	v_mov_b32_e32 v251, 0xf149f2ca
	v_mov_b32_e32 v248, 0xf149f2ca
	v_mov_b32_e32 v249, 0xf149f2ca
	v_mov_b32_e32 v246, 0xf149f2ca
	v_mov_b32_e32 v247, 0xf149f2ca
	v_mov_b32_e32 v244, 0xf149f2ca
	v_mov_b32_e32 v245, 0xf149f2ca
	v_mov_b32_e32 v242, 0xf149f2ca
	v_mov_b32_e32 v243, 0xf149f2ca
	v_mov_b32_e32 v240, 0xf149f2ca
	v_mov_b32_e32 v241, 0xf149f2ca
	v_mov_b32_e32 v238, 0xf149f2ca
	v_mov_b32_e32 v239, 0xf149f2ca
	v_mov_b32_e32 v236, 0xf149f2ca
	v_mov_b32_e32 v237, 0xf149f2ca
	v_mov_b32_e32 v234, 0xf149f2ca
	v_mov_b32_e32 v235, 0xf149f2ca
	v_mov_b32_e32 v232, 0xf149f2ca
	v_mov_b32_e32 v233, 0xf149f2ca
	v_mov_b32_e32 v230, 0xf149f2ca
	v_mov_b32_e32 v231, 0xf149f2ca
	v_mov_b32_e32 v176, 0xf149f2ca
	v_mov_b32_e32 v229, 0xf149f2ca
	s_and_saveexec_b64 s[16:17], s[34:35]
	s_cbranch_execz .LBB0_518
	ds_read_b32 v229, v226 offset:124
	ds_read_b32 v176, v226 offset:128
	ds_read_b32 v231, v226 offset:132
	ds_read_b32 v230, v226 offset:136
	ds_read_b32 v233, v226 offset:156
	ds_read_b32 v232, v226 offset:160
	ds_read_b32 v235, v226 offset:164
	ds_read_b32 v234, v226 offset:168
	ds_read_b32 v237, v226 offset:188
	ds_read_b32 v236, v226 offset:192
	ds_read_b32 v239, v226 offset:196
	ds_read_b32 v238, v226 offset:200
	ds_read_b32 v241, v226 offset:220
	ds_read_b32 v240, v226 offset:224
	ds_read_b32 v243, v226 offset:228
	s_mov_b64 vcc, s[96:97]
	s_waitcnt lgkmcnt(14)
	v_add_f32_e32 v229, v96, v229
	ds_read_b32 v242, v226 offset:232
	v_mov_b32_e32 v96, 0xf149f2ca
	v_cndmask_b32_e32 v229, v96, v229, vcc
	s_mov_b64 vcc, s[14:15]
	s_waitcnt lgkmcnt(14)
	v_add_f32_e32 v176, v97, v176
	ds_read_b32 v245, v226 offset:252
	v_cndmask_b32_e32 v176, v96, v176, vcc
	s_mov_b64 vcc, s[12:13]
	s_waitcnt lgkmcnt(14)
	v_add_f32_e32 v231, v98, v231
	ds_read_b32 v244, v226 offset:256
	v_cndmask_b32_e32 v231, v96, v231, vcc
	s_mov_b64 vcc, s[10:11]
	s_waitcnt lgkmcnt(14)
	v_add_f32_e32 v230, v99, v230
	ds_read_b32 v247, v226 offset:260
	v_cndmask_b32_e32 v230, v96, v230, vcc
	s_mov_b64 vcc, s[8:9]
	s_waitcnt lgkmcnt(14)
	v_add_f32_e32 v233, v100, v233
	ds_read_b32 v246, v226 offset:264
	v_cndmask_b32_e32 v233, v96, v233, vcc
	s_mov_b64 vcc, s[6:7]
	s_waitcnt lgkmcnt(14)
	v_add_f32_e32 v232, v101, v232
	ds_read_b32 v249, v226 offset:284
	v_cndmask_b32_e32 v232, v96, v232, vcc
	s_mov_b64 vcc, s[94:95]
	s_waitcnt lgkmcnt(14)
	v_add_f32_e32 v235, v102, v235
	ds_read_b32 v248, v226 offset:288
	v_cndmask_b32_e32 v235, v96, v235, vcc
	s_mov_b64 vcc, s[92:93]
	s_waitcnt lgkmcnt(14)
	v_add_f32_e32 v234, v103, v234
	ds_read_b32 v251, v226 offset:292
	v_cndmask_b32_e32 v234, v96, v234, vcc
	s_mov_b64 vcc, s[90:91]
	s_waitcnt lgkmcnt(14)
	v_add_f32_e32 v237, v104, v237
	ds_read_b32 v250, v226 offset:296
	v_cndmask_b32_e32 v237, v96, v237, vcc
	s_mov_b64 vcc, s[88:89]
	s_waitcnt lgkmcnt(14)
	v_add_f32_e32 v236, v105, v236
	ds_read_b32 v200, v226 offset:316
	v_cndmask_b32_e32 v236, v96, v236, vcc
	s_mov_b64 vcc, s[86:87]
	s_waitcnt lgkmcnt(14)
	v_add_f32_e32 v239, v106, v239
	ds_read_b32 v199, v226 offset:320
	v_cndmask_b32_e32 v239, v96, v239, vcc
	s_mov_b64 vcc, s[84:85]
	s_waitcnt lgkmcnt(14)
	v_add_f32_e32 v238, v107, v238
	ds_read_b32 v181, v226 offset:324
	v_cndmask_b32_e32 v238, v96, v238, vcc
	s_mov_b64 vcc, s[82:83]
	s_waitcnt lgkmcnt(14)
	v_add_f32_e32 v241, v108, v241
	ds_read_b32 v201, v226 offset:328
	v_cndmask_b32_e32 v241, v96, v241, vcc
	s_mov_b64 vcc, s[80:81]
	s_waitcnt lgkmcnt(14)
	v_add_f32_e32 v240, v109, v240
	ds_read_b32 v178, v226 offset:348
	v_cndmask_b32_e32 v240, v96, v240, vcc
	s_mov_b64 vcc, s[78:79]
	s_waitcnt lgkmcnt(14)
	v_add_f32_e32 v243, v110, v243
	ds_read_b32 v205, v226 offset:352
	v_cndmask_b32_e32 v243, v96, v243, vcc
	s_mov_b64 vcc, s[76:77]
	s_waitcnt lgkmcnt(14)
	v_add_f32_e32 v242, v111, v242
	ds_read_b32 v198, v226 offset:356
	v_cndmask_b32_e32 v242, v96, v242, vcc
	s_mov_b64 vcc, s[74:75]
	s_waitcnt lgkmcnt(14)
	v_add_f32_e32 v245, v80, v245
	ds_read_b32 v180, v226 offset:360
	v_cndmask_b32_e32 v245, v96, v245, vcc
	s_mov_b64 vcc, s[72:73]
	s_waitcnt lgkmcnt(14)
	v_add_f32_e32 v244, v81, v244
	v_cndmask_b32_e32 v244, v96, v244, vcc
	s_mov_b64 vcc, s[70:71]
	s_waitcnt lgkmcnt(13)
	v_add_f32_e32 v247, v82, v247
	v_cndmask_b32_e32 v247, v96, v247, vcc
	s_mov_b64 vcc, s[68:69]
	s_waitcnt lgkmcnt(12)
	v_add_f32_e32 v246, v83, v246
	v_cndmask_b32_e32 v246, v96, v246, vcc
	s_mov_b64 vcc, s[66:67]
	s_waitcnt lgkmcnt(11)
	v_add_f32_e32 v249, v84, v249
	v_cndmask_b32_e32 v249, v96, v249, vcc
	s_mov_b64 vcc, s[64:65]
	s_waitcnt lgkmcnt(10)
	v_add_f32_e32 v248, v85, v248
	v_cndmask_b32_e32 v248, v96, v248, vcc
	s_mov_b64 vcc, s[62:63]
	s_waitcnt lgkmcnt(9)
	v_add_f32_e32 v251, v86, v251
	v_cndmask_b32_e32 v251, v96, v251, vcc
	s_mov_b64 vcc, s[18:19]
	s_waitcnt lgkmcnt(8)
	v_add_f32_e32 v250, v87, v250
	v_cndmask_b32_e32 v250, v96, v250, vcc
	s_mov_b64 vcc, s[56:57]
	s_waitcnt lgkmcnt(7)
	v_add_f32_e32 v200, v88, v200
	v_cndmask_b32_e32 v200, v96, v200, vcc
	s_mov_b64 vcc, s[52:53]
	s_waitcnt lgkmcnt(6)
	v_add_f32_e32 v199, v89, v199
	v_cndmask_b32_e32 v199, v96, v199, vcc
	s_mov_b64 vcc, s[50:51]
	s_waitcnt lgkmcnt(5)
	v_add_f32_e32 v181, v90, v181
	v_cndmask_b32_e32 v181, v96, v181, vcc
	s_mov_b64 vcc, s[46:47]
	s_waitcnt lgkmcnt(4)
	v_add_f32_e32 v201, v91, v201
	v_cndmask_b32_e32 v201, v96, v201, vcc
	s_mov_b64 vcc, s[48:49]
	s_waitcnt lgkmcnt(3)
	v_add_f32_e32 v178, v92, v178
	v_cndmask_b32_e32 v178, v96, v178, vcc
	s_mov_b64 vcc, s[60:61]
	s_waitcnt lgkmcnt(2)
	v_add_f32_e32 v205, v93, v205
	v_cndmask_b32_e32 v205, v96, v205, vcc
	s_mov_b64 vcc, s[58:59]
	s_waitcnt lgkmcnt(1)
	v_add_f32_e32 v198, v94, v198
	v_cndmask_b32_e32 v198, v96, v198, vcc
	s_mov_b64 vcc, s[54:55]
	s_waitcnt lgkmcnt(0)
	v_add_f32_e32 v180, v95, v180
	v_cndmask_b32_e32 v180, v96, v180, vcc

.LBB0_527:
	ds_read_b128 v[64:67], v208 offset:49152
	ds_read_b128 v[68:71], v208 offset:57344
	v_readlane_b32 s20, v255, 63
	s_cmpk_lt_i32 s20, 0x140
	s_movk_i32 s21, 0x1fff
	s_waitcnt lgkmcnt(1)
	v_mfma_f32_32x32x16_bf16 v[80:95], v[64:67], v[120:123], 0
	v_mov_b32_e32 v198, 0xbf1f24be
	s_waitcnt lgkmcnt(0)
	v_mfma_f32_32x32x16_bf16 v[64:79], v[68:71], v[120:123], 0
	ds_read_b128 v[120:123], v213 offset:49152
	s_waitcnt vmcnt(3)
	ds_read_b128 v[144:147], v213 offset:57344
	s_waitcnt lgkmcnt(1)
	v_mfma_f32_32x32x16_bf16 v[80:95], v[120:123], v[112:115], v[80:95]
	s_waitcnt lgkmcnt(0)
	v_mfma_f32_32x32x16_bf16 v[64:79], v[144:147], v[112:115], v[64:79]
	ds_read_b128 v[112:115], v214 offset:49152
	ds_read_b128 v[120:123], v214 offset:57344
	s_waitcnt lgkmcnt(1)
	v_mfma_f32_32x32x16_bf16 v[80:95], v[112:115], v[132:135], v[80:95]
	ds_read_b128 v[112:115], v215 offset:49152
	s_waitcnt lgkmcnt(1)
	v_mfma_f32_32x32x16_bf16 v[64:79], v[120:123], v[132:135], v[64:79]
	ds_read_b128 v[120:123], v215 offset:57344
	s_waitcnt lgkmcnt(1)
	v_mfma_f32_32x32x16_bf16 v[80:95], v[112:115], v[140:143], v[80:95]
	ds_read_b128 v[112:115], v216 offset:49152
	s_waitcnt lgkmcnt(1)
	v_mfma_f32_32x32x16_bf16 v[64:79], v[120:123], v[140:143], v[64:79]
	ds_read_b128 v[120:123], v216 offset:57344
	s_waitcnt lgkmcnt(1)
	v_mfma_f32_32x32x16_bf16 v[80:95], v[112:115], v[136:139], v[80:95]
	ds_read_b128 v[112:115], v217 offset:49152
	s_waitcnt lgkmcnt(1)
	v_mfma_f32_32x32x16_bf16 v[64:79], v[120:123], v[136:139], v[64:79]
	ds_read_b128 v[120:123], v217 offset:57344
	s_waitcnt lgkmcnt(1)
	v_mfma_f32_32x32x16_bf16 v[80:95], v[112:115], v[128:131], v[80:95]
	ds_read_b128 v[112:115], v218 offset:49152
	s_waitcnt lgkmcnt(1)
	v_mfma_f32_32x32x16_bf16 v[64:79], v[120:123], v[128:131], v[64:79]
	ds_read_b128 v[120:123], v218 offset:57344
	s_waitcnt lgkmcnt(1)
	v_mfma_f32_32x32x16_bf16 v[80:95], v[112:115], v[124:127], v[80:95]
	ds_read_b128 v[112:115], v219 offset:49152
	s_waitcnt lgkmcnt(1)
	v_mfma_f32_32x32x16_bf16 v[64:79], v[120:123], v[124:127], v[64:79]
	ds_read_b128 v[120:123], v219 offset:57344
	s_waitcnt lgkmcnt(1)
	v_mfma_f32_32x32x16_bf16 v[80:95], v[112:115], v[116:119], v[80:95]
	s_waitcnt lgkmcnt(0)
	v_mfma_f32_32x32x16_bf16 v[64:79], v[120:123], v[116:119], v[64:79]
	s_cbranch_scc1 .LBB0_595
	s_add_i32 s20, s38, s33
	s_add_i32 s20, s20, -5
	v_cmp_ge_i32_e32 vcc, s20, v223
	v_cmp_lt_i32_e64 s[16:17], s20, v224
	s_and_b64 s[38:39], vcc, s[16:17]
	v_mov_b32_e32 v127, 0xf149f2ca
	v_mov_b32_e32 v128, 0xf149f2ca
	v_mov_b32_e32 v125, 0xf149f2ca
	v_mov_b32_e32 v126, 0xf149f2ca
	v_mov_b32_e32 v123, 0xf149f2ca
	v_mov_b32_e32 v124, 0xf149f2ca
	v_mov_b32_e32 v120, 0xf149f2ca
	v_mov_b32_e32 v121, 0xf149f2ca
	v_mov_b32_e32 v118, 0xf149f2ca
	v_mov_b32_e32 v119, 0xf149f2ca
	v_mov_b32_e32 v116, 0xf149f2ca
	v_mov_b32_e32 v117, 0xf149f2ca
	v_mov_b32_e32 v114, 0xf149f2ca
	v_mov_b32_e32 v115, 0xf149f2ca
	v_mov_b32_e32 v112, 0xf149f2ca
	v_mov_b32_e32 v113, 0xf149f2ca
	v_mov_b32_e32 v143, 0xf149f2ca
	v_mov_b32_e32 v144, 0xf149f2ca
	v_mov_b32_e32 v141, 0xf149f2ca
	v_mov_b32_e32 v142, 0xf149f2ca
	v_mov_b32_e32 v139, 0xf149f2ca
	v_mov_b32_e32 v140, 0xf149f2ca
	v_mov_b32_e32 v137, 0xf149f2ca
	v_mov_b32_e32 v138, 0xf149f2ca
	v_mov_b32_e32 v135, 0xf149f2ca
	v_mov_b32_e32 v136, 0xf149f2ca
	v_mov_b32_e32 v133, 0xf149f2ca
	v_mov_b32_e32 v134, 0xf149f2ca
	v_mov_b32_e32 v131, 0xf149f2ca
	v_mov_b32_e32 v132, 0xf149f2ca
	v_mov_b32_e32 v129, 0xf149f2ca
	v_mov_b32_e32 v130, 0xf149f2ca
	s_and_saveexec_b64 s[16:17], s[38:39]
	s_cbranch_execz .LBB0_594
	v_sub_u32_e32 v112, v221, v220
	v_sub_u32_e32 v113, s20, v222
	s_movk_i32 s1, 0x7c
	v_mul_lo_u32 v113, v113, s1
	v_lshlrev_b32_e32 v112, 2, v112
	v_readlane_b32 s1, v254, 35
	s_nop 1
	v_add3_u32 v122, s1, v113, v112
	ds_read_b32 v113, v122 offset:60
	ds_read_b32 v112, v122 offset:64
	ds_read_b32 v115, v122 offset:68
	ds_read_b32 v114, v122 offset:72
	ds_read_b32 v117, v122 offset:92
	ds_read_b32 v116, v122 offset:96
	ds_read_b32 v119, v122 offset:100
	ds_read_b32 v118, v122 offset:104
	ds_read_b32 v121, v122 offset:124
	ds_read_b32 v120, v122 offset:128
	ds_read_b32 v124, v122 offset:132
	ds_read_b32 v123, v122 offset:136
	ds_read_b32 v126, v122 offset:156
	ds_read_b32 v125, v122 offset:160
	ds_read_b32 v128, v122 offset:164
	s_mov_b64 vcc, s[96:97]
	s_waitcnt lgkmcnt(14)
	v_add_f32_e32 v113, v80, v113
	ds_read_b32 v127, v122 offset:168
	v_mov_b32_e32 v80, 0xf149f2ca
	v_cndmask_b32_e32 v113, v80, v113, vcc
	s_mov_b64 vcc, s[14:15]
	s_waitcnt lgkmcnt(14)
	v_add_f32_e32 v112, v81, v112
	ds_read_b32 v130, v122 offset:188
	v_cndmask_b32_e32 v112, v80, v112, vcc
	s_mov_b64 vcc, s[12:13]
	s_waitcnt lgkmcnt(14)
	v_add_f32_e32 v115, v82, v115
	ds_read_b32 v129, v122 offset:192
	v_cndmask_b32_e32 v115, v80, v115, vcc
	s_mov_b64 vcc, s[10:11]
	s_waitcnt lgkmcnt(14)
	v_add_f32_e32 v114, v83, v114
	ds_read_b32 v132, v122 offset:196
	v_cndmask_b32_e32 v114, v80, v114, vcc
	s_mov_b64 vcc, s[8:9]
	s_waitcnt lgkmcnt(14)
	v_add_f32_e32 v117, v84, v117
	ds_read_b32 v131, v122 offset:200
	v_cndmask_b32_e32 v117, v80, v117, vcc
	s_mov_b64 vcc, s[6:7]
	s_waitcnt lgkmcnt(14)
	v_add_f32_e32 v116, v85, v116
	ds_read_b32 v134, v122 offset:220
	v_cndmask_b32_e32 v116, v80, v116, vcc
	s_mov_b64 vcc, s[94:95]
	s_waitcnt lgkmcnt(14)
	v_add_f32_e32 v119, v86, v119
	ds_read_b32 v133, v122 offset:224
	v_cndmask_b32_e32 v119, v80, v119, vcc
	s_mov_b64 vcc, s[92:93]
	s_waitcnt lgkmcnt(14)
	v_add_f32_e32 v118, v87, v118
	ds_read_b32 v136, v122 offset:228
	v_cndmask_b32_e32 v118, v80, v118, vcc
	s_mov_b64 vcc, s[90:91]
	s_waitcnt lgkmcnt(14)
	v_add_f32_e32 v121, v88, v121
	ds_read_b32 v135, v122 offset:232
	v_cndmask_b32_e32 v121, v80, v121, vcc
	s_mov_b64 vcc, s[88:89]
	s_waitcnt lgkmcnt(14)
	v_add_f32_e32 v120, v89, v120
	ds_read_b32 v138, v122 offset:252
	v_cndmask_b32_e32 v120, v80, v120, vcc
	s_mov_b64 vcc, s[86:87]
	s_waitcnt lgkmcnt(14)
	v_add_f32_e32 v124, v90, v124
	ds_read_b32 v137, v122 offset:256
	v_cndmask_b32_e32 v124, v80, v124, vcc
	s_mov_b64 vcc, s[84:85]
	s_waitcnt lgkmcnt(14)
	v_add_f32_e32 v123, v91, v123
	ds_read_b32 v140, v122 offset:260
	v_cndmask_b32_e32 v123, v80, v123, vcc
	s_mov_b64 vcc, s[82:83]
	s_waitcnt lgkmcnt(14)
	v_add_f32_e32 v126, v92, v126
	ds_read_b32 v139, v122 offset:264
	v_cndmask_b32_e32 v126, v80, v126, vcc
	s_mov_b64 vcc, s[80:81]
	s_waitcnt lgkmcnt(14)
	v_add_f32_e32 v125, v93, v125
	ds_read_b32 v142, v122 offset:284
	v_cndmask_b32_e32 v125, v80, v125, vcc
	s_mov_b64 vcc, s[78:79]
	s_waitcnt lgkmcnt(14)
	v_add_f32_e32 v128, v94, v128
	ds_read_b32 v141, v122 offset:288
	v_cndmask_b32_e32 v128, v80, v128, vcc
	s_mov_b64 vcc, s[76:77]
	s_waitcnt lgkmcnt(14)
	v_add_f32_e32 v127, v95, v127
	ds_read_b32 v144, v122 offset:292
	v_cndmask_b32_e32 v127, v80, v127, vcc
	s_mov_b64 vcc, s[74:75]
	s_waitcnt lgkmcnt(14)
	v_add_f32_e32 v130, v64, v130
	ds_read_b32 v143, v122 offset:296
	v_cndmask_b32_e32 v130, v80, v130, vcc
	s_mov_b64 vcc, s[72:73]
	s_waitcnt lgkmcnt(14)
	v_add_f32_e32 v129, v65, v129
	v_cndmask_b32_e32 v129, v80, v129, vcc
	s_mov_b64 vcc, s[70:71]
	s_waitcnt lgkmcnt(13)
	v_add_f32_e32 v132, v66, v132
	v_cndmask_b32_e32 v132, v80, v132, vcc
	s_mov_b64 vcc, s[68:69]
	s_waitcnt lgkmcnt(12)
	v_add_f32_e32 v131, v67, v131
	v_cndmask_b32_e32 v131, v80, v131, vcc
	s_mov_b64 vcc, s[66:67]
	s_waitcnt lgkmcnt(11)
	v_add_f32_e32 v134, v68, v134
	v_cndmask_b32_e32 v134, v80, v134, vcc
	s_mov_b64 vcc, s[64:65]
	s_waitcnt lgkmcnt(10)
	v_add_f32_e32 v133, v69, v133
	v_cndmask_b32_e32 v133, v80, v133, vcc
	s_mov_b64 vcc, s[62:63]
	s_waitcnt lgkmcnt(9)
	v_add_f32_e32 v136, v70, v136
	v_cndmask_b32_e32 v136, v80, v136, vcc
	s_mov_b64 vcc, s[18:19]
	s_waitcnt lgkmcnt(8)
	v_add_f32_e32 v135, v71, v135
	v_cndmask_b32_e32 v135, v80, v135, vcc
	s_mov_b64 vcc, s[56:57]
	s_waitcnt lgkmcnt(7)
	v_add_f32_e32 v138, v72, v138
	v_cndmask_b32_e32 v138, v80, v138, vcc
	s_mov_b64 vcc, s[52:53]
	s_waitcnt lgkmcnt(6)
	v_add_f32_e32 v137, v73, v137
	v_cndmask_b32_e32 v137, v80, v137, vcc
	s_mov_b64 vcc, s[50:51]
	s_waitcnt lgkmcnt(5)
	v_add_f32_e32 v140, v74, v140
	v_cndmask_b32_e32 v140, v80, v140, vcc
	s_mov_b64 vcc, s[46:47]
	s_waitcnt lgkmcnt(4)
	v_add_f32_e32 v139, v75, v139
	v_cndmask_b32_e32 v139, v80, v139, vcc
	s_mov_b64 vcc, s[48:49]
	s_waitcnt lgkmcnt(3)
	v_add_f32_e32 v142, v76, v142
	v_cndmask_b32_e32 v142, v80, v142, vcc
	s_mov_b64 vcc, s[60:61]
	s_waitcnt lgkmcnt(2)
	v_add_f32_e32 v141, v77, v141
	v_cndmask_b32_e32 v141, v80, v141, vcc
	s_mov_b64 vcc, s[58:59]
	s_waitcnt lgkmcnt(1)
	v_add_f32_e32 v144, v78, v144
	v_cndmask_b32_e32 v144, v80, v144, vcc
	s_mov_b64 vcc, s[54:55]
	s_waitcnt lgkmcnt(0)
	v_add_f32_e32 v143, v79, v143
	v_cndmask_b32_e32 v143, v80, v143, vcc
